# attention key tiles via LDS-DMA (row-contiguous, swizzled, one tile ahead); one attention loop for both workgroup classes
# speedup vs baseline: 1.0051x; 1.0051x over previous
; #define ATT_LOAD(K_, V_, kb_) do { _Pragma("unroll") for (int ks = 0; ks < 4; ++ks) K_[ks] = *(const bf16x8_t*)(kbase + (size_t)(32 * (kb_)) * 1024 + 16 * ks); \
;         _Pragma("unroll") for (int i = 0; i < 4; ++i) V_[i] = *(const bf16x8_t*)(vbase + (size_t)(32 * (i >> 1)) * 2048 + 32 * (kb_) + 16 * (i & 1)); } while (0)
; __device__ __forceinline__ void attn_mfma(const Args& a, int u0, int ucnt, int ustride) {
;     unsigned char* ws = a.ws;
;     bf16* QS = (bf16*)(ws + WS_QS); const bf16* SK = (const bf16*)(ws + WS_SK); const bf16* VT = (const bf16*)((unsigned char*)a.out + 32 * MiB);
;     const int lane = threadIdx.x & 63, r32 = lane & 31, hi = lane >> 5;
;     const int kap = 16 * (r32 >> 4) + 8 * ((r32 >> 2) & 1) + 4 * ((r32 >> 3) & 1) + (r32 & 3);
;     for (int uk = 0; uk < ucnt; ++uk) { const int u = u0 + uk * ustride;
;         const int qb = u & 63, bh = u >> 6, h = bh & 15, b = bh >> 4;
;         const size_t rowq = (size_t)b * SEQ + 32 * qb + r32;
;         bf16* qp = QS + rowq * 2048 + 1024 + 64 * h;
;         const bf16* kbase = SK + ((size_t)b * SEQ + kap) * 1024 + 64 * h + 8 * hi;
;         const bf16* vbase = VT + ((size_t)bh * 64 + r32) * 2048 + 8 * hi;
;         bf16x8_t Qf[4];
; #pragma unroll
;         for (int ks = 0; ks < 4; ++ks) Qf[ks] = *(const bf16x8_t*)(qp + 16 * ks + 8 * hi);
;         f32x16 O0, O1;
; #pragma unroll
;         for (int j = 0; j < 16; ++j) { O0[j] = 0.f; O1[j] = 0.f; }
;         float carry = 1.f;
;         bf16x8_t KA[4], VA[4], KB[4], VB[4];
;     ...
;         ATT_LOAD(KA, VA, qb);
;         int kb = qb;
;         ATT_LOAD(KB, VB, kb > 0 ? kb - 1 : 0);
; __global__ void __launch_bounds__(NTHREADS, 2) hybrid_fwd(Args args) {
;     ...
;             else { const int idx = (int)blockIdx.x - 64;
;                 if (idx < 128) attn_mfma(args, idx * 40 + wave, 5, NWAVES); else attn_mfma(args, 5120 + (idx - 128) * 48 + wave, 6, NWAVES);
.LBB0_396:
	s_and_b64 vcc, exec, s[0:1]
	s_cbranch_vccz .LBB0_722
	s_cmp_gt_i32 s33, 63
	s_cbranch_scc0 .LBB0_406
	s_cmpk_lt_u32 s33, 0xc0
	s_cselect_b64 s[38:39], -1, 0
	s_cmpk_gt_u32 s33, 0xbf
	s_cselect_b64 s[0:1], -1, 0
	s_mov_b64 s[2:3], -1
	s_and_b64 vcc, exec, s[0:1]
	s_mul_i32 s2, s33, 48
	v_readlane_b32 s3, v254, 11
	s_add_i32 s44, s2, s3
	s_waitcnt vmcnt(0)
	v_lshlrev_b32_e32 v1, 1, v188
	v_lshrrev_b32_e32 v2, 1, v188
	v_and_b32_e32 v82, 31, v188
	v_readlane_b32 s2, v254, 22
	v_and_b32_e32 v0, 19, v188
	v_and_b32_e32 v1, 8, v1
	v_and_b32_e32 v2, 4, v2
	v_bfe_u32 v3, v188, 5, 1
	v_mov_b32_e32 v85, 0
	v_lshlrev_b32_e32 v84, 12, v82
	v_readlane_b32 s3, v254, 23
	v_or3_b32 v80, v1, v0, v2
	v_lshlrev_b32_e32 v2, 3, v3
	v_lshl_add_u64 v[0:1], s[2:3], 0, v[84:85]
	v_lshlrev_b32_e32 v84, 4, v3
	v_lshl_add_u64 v[86:87], v[0:1], 0, v[84:85]
	v_or_b32_e32 v0, 1, v2
	v_cmp_lt_u32_e64 s[4:5], v0, v82
	v_or_b32_e32 v0, 3, v2
	v_cmp_lt_u32_e64 s[6:7], v0, v82
	v_or_b32_e32 v0, 5, v2
	v_cmp_lt_u32_e64 s[10:11], v0, v82
	v_or_b32_e32 v0, 6, v2
	v_cmp_lt_u32_e64 s[14:15], v0, v82
	v_or_b32_e32 v0, 7, v2
	v_cmp_lt_u32_e64 s[16:17], v0, v82
	v_or_b32_e32 v0, 17, v2
	v_cmp_lt_u32_e64 s[18:19], v0, v82
	v_or_b32_e32 v0, 19, v2
	v_cmp_lt_u32_e64 s[22:23], v0, v82
	v_or_b32_e32 v0, 21, v2
	v_or_b32_e32 v1, 2, v2
	v_cmp_lt_u32_e64 s[26:27], v0, v82
	v_or_b32_e32 v0, 22, v2
	v_cmp_lt_u32_e64 s[8:9], v1, v82
	v_or_b32_e32 v1, 4, v2
	v_cmp_lt_u32_e64 s[30:31], v0, v82
	v_or_b32_e32 v0, 23, v2
	v_cmp_lt_u32_e64 s[12:13], v1, v82
	v_or_b32_e32 v1, 16, v2
	v_cmp_lt_u32_e64 s[34:35], v0, v82
	v_mbcnt_lo_u32_b32 v0, -1, 0
	v_cmp_lt_u32_e64 s[20:21], v1, v82
	v_or_b32_e32 v1, 18, v2
	v_mbcnt_hi_u32_b32 v0, -1, v0
	v_cmp_lt_u32_e64 s[24:25], v1, v82
	v_or_b32_e32 v1, 20, v2
	v_and_b32_e32 v4, 64, v0
	v_cmp_lt_u32_e64 s[28:29], v1, v82
	v_xor_b32_e32 v1, 32, v0
	v_add_u32_e32 v4, 64, v4
	v_cmp_lt_i32_e32 vcc, v1, v4
	s_addk_i32 s44, 0xf000
	v_cmp_lt_u32_e64 s[2:3], v2, v82
	v_cndmask_b32_e32 v0, v0, v1, vcc
	v_lshlrev_b32_e32 v81, 2, v0
	v_lshlrev_b32_e32 v0, 2, v3
	s_mov_b32 s41, 0
	v_cmp_eq_u32_e64 s[36:37], 0, v3
	v_lshlrev_b32_e32 v88, 1, v2
	v_mov_b32_e32 v89, v85
	s_mov_b32 s45, 0x8000
	v_lshlrev_b32_e32 v84, 1, v0
	s_mov_b32 s46, 0
	v_mbcnt_lo_u32_b32 v189, -1, 0
	v_mbcnt_hi_u32_b32 v189, -1, v189
	v_readlane_b32 s78, v254, 11
	v_readlane_b32 s92, v254, 22
	v_readlane_b32 s93, v254, 23
	s_nop 0
	s_lshl_b32 s78, s78, 14
	v_lshrrev_b32_e32 v206, 3, v189
	v_and_b32_e32 v207, 7, v189
	v_lshrrev_b32_e32 v208, 1, v206
	v_xor_b32_e32 v209, v207, v208
	v_xor_b32_e32 v210, 4, v209
	v_lshlrev_b32_e32 v209, 4, v209
	v_lshlrev_b32_e32 v210, 4, v210
	v_lshl_add_u32 v190, v206, 11, v209
	v_lshl_add_u32 v191, v206, 11, v210
	v_add_u32_e32 v191, 0x3c00, v191
	v_add_u32_e32 v192, 0x7800, v190
	v_add_u32_e32 v193, 0x7800, v191
	v_lshrrev_b32_e32 v206, 2, v189
	v_and_b32_e32 v207, 3, v189
	v_bfe_u32 v208, v189, 4, 2
	v_xor_b32_e32 v207, v207, v208
	v_lshlrev_b32_e32 v207, 4, v207
	v_lshl_add_u32 v194, v206, 12, v207
	v_add_u32_e32 v195, 0xfc00, v194
	v_add_u32_e32 v196, 0x1f800, v194
	v_add_u32_e32 v197, 0x2f400, v194
	v_lshrrev_b32_e32 v206, 5, v189
	v_bfe_u32 v207, v80, 1, 3
	v_xor_b32_e32 v207, v207, v206
	v_lshlrev_b32_e32 v208, 3, v80
	v_or_b32_e32 v209, v208, v207
	v_lshl_add_u32 v198, v209, 4, s78
	v_xor_b32_e32 v210, 2, v207
	v_or_b32_e32 v210, v208, v210
	v_lshl_add_u32 v199, v210, 4, s78
	v_xor_b32_e32 v210, 4, v207
	v_or_b32_e32 v210, v208, v210
	v_lshl_add_u32 v200, v210, 4, s78
	v_xor_b32_e32 v210, 6, v207
	v_or_b32_e32 v210, v208, v210
	v_lshl_add_u32 v201, v210, 4, s78
	v_bfe_u32 v207, v82, 2, 2
	v_xor_b32_e32 v207, v207, v206
	v_lshlrev_b32_e32 v208, 2, v82
	v_or_b32_e32 v209, v208, v207
	v_lshl_add_u32 v202, v209, 4, s78
	v_add_u32_e32 v202, 0x1000, v202
	v_xor_b32_e32 v210, 2, v207
	v_or_b32_e32 v210, v208, v210
	v_lshl_add_u32 v203, v210, 4, s78
	v_add_u32_e32 v203, 0x1000, v203
	v_add_u32_e32 v204, 0x800, v202
	v_add_u32_e32 v205, 0x800, v203
	s_mov_b32 s101, 6
	s_cmpk_gt_u32 s33, 0xbf
	s_cbranch_scc1 .Latt_cls
	s_mul_i32 s44, s33, 40
	v_readlane_b32 s100, v254, 11
	s_addk_i32 s44, 0xf600
	s_add_i32 s44, s44, s100
	s_mov_b32 s101, 5

; __device__ __forceinline__ unsigned cvtpk(float lo, float hi) { const f32x2_t v = {lo, hi}; return __builtin_bit_cast(unsigned, __builtin_convertvector(v, bf16x2_cv)); }
; #define ATT_LOAD(K_, V_, kb_) do { _Pragma("unroll") for (int ks = 0; ks < 4; ++ks) K_[ks] = *(const bf16x8_t*)(kbase + (size_t)(32 * (kb_)) * 1024 + 16 * ks); \
;         _Pragma("unroll") for (int i = 0; i < 4; ++i) V_[i] = *(const bf16x8_t*)(vbase + (size_t)(32 * (i >> 1)) * 2048 + 32 * (kb_) + 16 * (i & 1)); } while (0)
; __device__ __forceinline__ void attn_mfma(const Args& a, int u0, int ucnt, int ustride) {
;     ...
;     for (int uk = 0; uk < ucnt; ++uk) { const int u = u0 + uk * ustride;
;         const int qb = u & 63, bh = u >> 6, h = bh & 15, b = bh >> 4;
;         const size_t rowq = (size_t)b * SEQ + 32 * qb + r32;
;         bf16* qp = QS + rowq * 2048 + 1024 + 64 * h;
;         const bf16* kbase = SK + ((size_t)b * SEQ + kap) * 1024 + 64 * h + 8 * hi;
;         const bf16* vbase = VT + ((size_t)bh * 64 + r32) * 2048 + 8 * hi;
;         bf16x8_t Qf[4];
; #pragma unroll
;         for (int ks = 0; ks < 4; ++ks) Qf[ks] = *(const bf16x8_t*)(qp + 16 * ks + 8 * hi);
;         f32x16 O0, O1;
; #pragma unroll
;         for (int j = 0; j < 16; ++j) { O0[j] = 0.f; O1[j] = 0.f; }
;         float carry = 1.f;
;         bf16x8_t KA[4], VA[4], KB[4], VB[4];
;     ...
;         ATT_LOAD(KA, VA, qb);
;         int kb = qb;
;         ATT_LOAD(KB, VB, kb > 0 ? kb - 1 : 0);
;     ...
; #pragma unroll
;         for (int a4 = 0; a4 < 4; ++a4) {
;             u32x2_t x0, x1; x0.x = cvtpk(O0[4 * a4], O0[4 * a4 + 1]); x0.y = cvtpk(O0[4 * a4 + 2], O0[4 * a4 + 3]); x1.x = cvtpk(O1[4 * a4], O1[4 * a4 + 1]); x1.y = cvtpk(O1[4 * a4 + 2], O1[4 * a4 + 3]);
;             *(u32x2_t*)(qp + 8 * a4 + 4 * hi) = x0; *(u32x2_t*)(qp + 32 + 8 * a4 + 4 * hi) = x1; }
.LBB0_400:
	v_lshl_add_u64 v[32:33], v[90:91], 0, v[84:85]
	s_nop 7
	v_cvt_pk_bf16_f32 v0, v0, v1
	v_cvt_pk_bf16_f32 v1, v2, v3
	v_cvt_pk_bf16_f32 v2, v16, v17
	v_cvt_pk_bf16_f32 v3, v18, v19
	global_store_dwordx2 v[32:33], v[0:1], off
	global_store_dwordx2 v[32:33], v[2:3], off offset:64
	v_cvt_pk_bf16_f32 v0, v4, v5
	v_cvt_pk_bf16_f32 v1, v6, v7
	v_cvt_pk_bf16_f32 v2, v20, v21
	v_cvt_pk_bf16_f32 v3, v22, v23
	global_store_dwordx2 v[32:33], v[0:1], off offset:16
	global_store_dwordx2 v[32:33], v[2:3], off offset:80
	v_cvt_pk_bf16_f32 v0, v8, v9
	v_cvt_pk_bf16_f32 v1, v10, v11
	v_cvt_pk_bf16_f32 v2, v24, v25
	v_cvt_pk_bf16_f32 v3, v26, v27
	s_add_i32 s46, s46, 1
	global_store_dwordx2 v[32:33], v[0:1], off offset:32
	global_store_dwordx2 v[32:33], v[2:3], off offset:96
	v_cvt_pk_bf16_f32 v0, v12, v13
	v_cvt_pk_bf16_f32 v1, v14, v15
	v_cvt_pk_bf16_f32 v2, v28, v29
	v_cvt_pk_bf16_f32 v3, v30, v31
	s_cmp_lg_u32 s46, s101
	global_store_dwordx2 v[32:33], v[0:1], off offset:48
	global_store_dwordx2 v[32:33], v[2:3], off offset:112
	s_cbranch_scc0 .LBB0_407
.LBB0_401:
	s_lshl_b32 s40, s46, 3
	s_add_i32 s40, s44, s40
	s_ashr_i32 s48, s40, 10
	s_and_b32 s47, s40, 63
	s_ashr_i32 s49, s48, 31
	s_lshl_b64 s[48:49], s[48:49], 11
	s_lshl_b32 s43, s47, 5
	s_or_b32 s43, s48, s43
	v_mov_b32_e32 v1, s49
	v_or_b32_e32 v0, s43, v82
	s_ashr_i32 s42, s40, 6
	v_lshlrev_b64 v[0:1], 12, v[0:1]
	s_and_b32 s40, s40, 0x3c0
	v_lshl_add_u64 v[0:1], s[72:73], 0, v[0:1]
	s_lshl_b32 s40, s40, 1
	v_lshl_add_u64 v[0:1], v[0:1], 0, s[40:41]
	s_mov_b64 s[76:77], 0x4b00800
	v_lshl_add_u64 v[90:91], v[0:1], 0, s[76:77]
	v_mov_b32_e32 v1, s49
	v_or_b32_e32 v0, s48, v80
	v_lshlrev_b64 v[0:1], 11, v[0:1]
	v_lshl_add_u64 v[0:1], s[90:91], 0, v[0:1]
	v_lshl_add_u64 v[0:1], v[0:1], 0, s[40:41]
	v_lshl_add_u64 v[92:93], v[0:1], 0, v[88:89]
	s_lshl_b32 s94, s48, 11
	s_add_u32 s80, s90, s94
	s_addc_u32 s81, s91, 0
	s_add_u32 s80, s80, s40
	s_addc_u32 s81, s81, 0
	s_lshl_b32 s94, s42, 18
	s_add_u32 s82, s92, s94
	s_addc_u32 s83, s93, 0
	v_lshl_add_u64 v[2:3], v[90:91], 0, v[88:89]
	global_load_dwordx4 v[48:51], v[2:3], off
	global_load_dwordx4 v[52:55], v[2:3], off offset:32
	global_load_dwordx4 v[56:59], v[2:3], off offset:64
	global_load_dwordx4 v[60:63], v[2:3], off offset:96
	s_lshl_b32 s94, s47, 16
	s_add_u32 s94, s80, s94
	s_addc_u32 s95, s81, 0
	s_lshl_b32 s96, s47, 6
	s_add_u32 s96, s82, s96
	s_addc_u32 s97, s83, 0
	s_add_i32 m0, s78, 0x0
	s_nop 0
	global_load_lds_dwordx4 v190, s[94:95]
	global_load_lds_dwordx4 v191, s[94:95] offset:1024
	global_load_lds_dwordx4 v192, s[94:95] offset:2048
	global_load_lds_dwordx4 v193, s[94:95] offset:3072
	s_add_i32 m0, s78, 0x1000
	s_nop 0
	global_load_lds_dwordx4 v194, s[96:97]
	global_load_lds_dwordx4 v195, s[96:97] offset:1024
	global_load_lds_dwordx4 v196, s[96:97] offset:2048
	global_load_lds_dwordx4 v197, s[96:97] offset:3072
	s_add_i32 s98, s47, -1
	s_max_i32 s98, s98, 0
	s_lshl_b32 s94, s98, 16
	s_add_u32 s94, s80, s94
	s_addc_u32 s95, s81, 0
	s_lshl_b32 s96, s98, 6
	s_add_u32 s96, s82, s96
	s_addc_u32 s97, s83, 0
	s_add_i32 m0, s78, 0x2000
	s_nop 0
	global_load_lds_dwordx4 v190, s[94:95]
	global_load_lds_dwordx4 v191, s[94:95] offset:1024
	global_load_lds_dwordx4 v192, s[94:95] offset:2048
	global_load_lds_dwordx4 v193, s[94:95] offset:3072
	s_add_i32 m0, s78, 0x3000
	s_nop 0
	global_load_lds_dwordx4 v194, s[96:97]
	global_load_lds_dwordx4 v195, s[96:97] offset:1024
	global_load_lds_dwordx4 v196, s[96:97] offset:2048
	global_load_lds_dwordx4 v197, s[96:97] offset:3072
	s_waitcnt vmcnt(8)
	ds_read_b128 v[0:3], v198
	ds_read_b128 v[28:31], v199
	ds_read_b128 v[36:39], v200
	ds_read_b128 v[40:43], v201
	ds_read_b128 v[24:27], v202
	ds_read_b128 v[20:23], v203
	ds_read_b128 v[16:19], v204
	ds_read_b128 v[32:35], v205
	s_waitcnt lgkmcnt(7)
	v_mfma_f32_32x32x16_bf16 v[0:15], v[0:3], v[48:51], 0
	s_waitcnt lgkmcnt(6)
	v_mfma_f32_32x32x16_bf16 v[0:15], v[28:31], v[52:55], v[0:15]
	s_waitcnt lgkmcnt(5)
	v_mfma_f32_32x32x16_bf16 v[0:15], v[36:39], v[56:59], v[0:15]
	s_waitcnt lgkmcnt(4)
	v_mfma_f32_32x32x16_bf16 v[0:15], v[40:43], v[60:63], v[0:15]
	s_nop 11
	v_exp_f32_e32 v2, v2
	v_exp_f32_e32 v0, v0
	v_exp_f32_e32 v1, v1
	v_add_f32_e32 v2, 1.0, v2
	v_rcp_f32_e32 v28, v2
	v_exp_f32_e32 v2, v3
	v_exp_f32_e32 v3, v7
	v_exp_f32_e32 v7, v15
	v_add_f32_e32 v0, 1.0, v0
	v_add_f32_e32 v2, 1.0, v2
	v_rcp_f32_e32 v29, v2
	v_exp_f32_e32 v2, v4
	v_add_f32_e32 v7, 1.0, v7
	v_rcp_f32_e32 v7, v7
	v_add_f32_e32 v3, 1.0, v3
	v_add_f32_e32 v2, 1.0, v2
	v_rcp_f32_e32 v4, v2
	v_exp_f32_e32 v2, v5
	v_rcp_f32_e32 v3, v3
	v_add_f32_e32 v1, 1.0, v1
	v_rcp_f32_e32 v0, v0
	v_add_f32_e32 v2, 1.0, v2
	v_rcp_f32_e32 v5, v2
	v_exp_f32_e32 v2, v6
	v_exp_f32_e32 v6, v8
	v_cndmask_b32_e64 v37, 1.0, v3, s[16:17]
	v_rcp_f32_e32 v1, v1
	v_add_f32_e32 v2, 1.0, v2
	v_add_f32_e32 v6, 1.0, v6
	v_rcp_f32_e32 v8, v6
	v_exp_f32_e32 v6, v9
	v_rcp_f32_e32 v2, v2
	v_sub_f32_e32 v3, 1.0, v3
	v_cndmask_b32_e64 v3, 0, v3, s[16:17]
	v_add_f32_e32 v6, 1.0, v6
	v_rcp_f32_e32 v9, v6
	v_exp_f32_e32 v6, v10
	v_cndmask_b32_e64 v36, 1.0, v2, s[14:15]
	v_sub_f32_e32 v2, 1.0, v2
	v_cndmask_b32_e64 v2, 0, v2, s[14:15]
	v_add_f32_e32 v6, 1.0, v6
	v_rcp_f32_e32 v30, v6
	v_exp_f32_e32 v6, v11
	v_mul_f32_e32 v2, v37, v2
	v_mul_f32_e32 v37, v36, v37
	v_cndmask_b32_e64 v39, 1.0, v30, s[24:25]
	v_add_f32_e32 v6, 1.0, v6
	v_rcp_f32_e32 v31, v6
	v_exp_f32_e32 v6, v12
	s_nop 0
	v_add_f32_e32 v6, 1.0, v6
	v_rcp_f32_e32 v10, v6
	v_exp_f32_e32 v6, v13
	v_cndmask_b32_e64 v13, 1.0, v7, s[34:35]
	v_sub_f32_e32 v7, 1.0, v7
	v_cndmask_b32_e64 v38, 1.0, v10, s[28:29]
	v_add_f32_e32 v6, 1.0, v6
	v_rcp_f32_e32 v11, v6
; __device__ __forceinline__ unsigned cvtpk(float lo, float hi) { const f32x2_t v = {lo, hi}; return __builtin_bit_cast(unsigned, __builtin_convertvector(v, bf16x2_cv)); }
; #define MFMA32(A, B, C) __builtin_amdgcn_mfma_f32_32x32x16_bf16((A), (B), (C), 0, 0, 0)
; template <bool DIAG> __device__ __forceinline__ bool attn_tile(const bf16x8_t (&Kc)[4], const bf16x8_t (&Vc)[4], const bf16x8_t (&Qf)[4], f32x16& O0, f32x16& O1, float& carry, int r32, int hi) {
;     ...
; #pragma unroll
;     for (int j = 0; j < 16; ++j) {
;         const float r = __builtin_amdgcn_rcpf(1.0f + __builtin_amdgcn_exp2f(Sx[j]));
;         if (DIAG) { const int sl = 16 * (j >> 3) + 8 * hi + (j & 7); const bool valid = sl < r32; kp[j] = valid ? r : 1.f; sg[j] = valid ? 1.0f - r : 0.f; }
;         else { kp[j] = r; sg[j] = 1.0f - r; }
;     }
; #pragma unroll
;     for (int j = 6; j >= 0; --j) { sg[j] *= kp[j + 1]; kp[j] *= kp[j + 1]; sg[8 + j] *= kp[8 + j + 1]; kp[8 + j] *= kp[8 + j + 1]; }
;     const float G0 = kp[0], G1 = kp[8];
;     const float P0 = __shfl_xor(G0, 32), P1 = __shfl_xor(G1, 32);
;     const float after0 = (hi == 0 ? P0 : 1.f) * P1 * G1 * carry, after1 = (hi == 0 ? P1 : 1.f) * carry;
; #pragma unroll
;     for (int j = 0; j < 16; ++j) sg[j] *= (j < 8 ? after0 : after1);
;     carry *= (G0 * G1) * (P0 * P1);
;     v4u w0, w1; w0.x = cvtpk(sg[0], sg[1]); w0.y = cvtpk(sg[2], sg[3]); w0.z = cvtpk(sg[4], sg[5]); w0.w = cvtpk(sg[6], sg[7]);
;     w1.x = cvtpk(sg[8], sg[9]); w1.y = cvtpk(sg[10], sg[11]); w1.z = cvtpk(sg[12], sg[13]); w1.w = cvtpk(sg[14], sg[15]);
;     const bf16x8_t Pb0 = __builtin_bit_cast(bf16x8_t, w0), Pb1 = __builtin_bit_cast(bf16x8_t, w1);
;     O0 = MFMA32(Vc[0], Pb0, O0); O0 = MFMA32(Vc[1], Pb1, O0);
;     O1 = MFMA32(Vc[2], Pb0, O1); O1 = MFMA32(Vc[3], Pb1, O1);
;     return __all(carry < 0x1p-134f);
; __device__ __forceinline__ void attn_mfma(const Args& a, int u0, int ucnt, int ustride) {
;     ...
;         if (!(attn_tile<true>(KA, VA, Qf, O0, O1, carry, r32, hi) || kb == 0)) {
;     ...
; #pragma unroll 1
;             for (;;) {
;                 ATT_LOAD(KA, VA, kb > 0 ? kb - 1 : 0);
;                 if (attn_tile<false>(KB, VB, Qf, O0, O1, carry, r32, hi) || kb == 0) break;
	v_exp_f32_e32 v6, v14
	v_cndmask_b32_e64 v7, 0, v7, s[34:35]
	v_cndmask_b32_e64 v14, 1.0, v11, s[26:27]
	v_add_f32_e32 v6, 1.0, v6
	v_rcp_f32_e32 v6, v6
	v_pk_add_f32 v[10:11], v[10:11], 1.0 op_sel_hi:[1,0] neg_lo:[1,0] neg_hi:[1,0]
	v_cndmask_b32_e64 v12, 1.0, v6, s[30:31]
	v_sub_f32_e32 v6, 1.0, v6
	v_cndmask_b32_e64 v6, 0, v6, s[30:31]
	v_mul_f32_e32 v6, v13, v6
	v_mul_f32_e32 v13, v12, v13
	v_cndmask_b32_e64 v11, 0, v11, s[26:27]
	v_cndmask_b32_e64 v10, 0, v10, s[28:29]
	v_mul_f32_e32 v12, v14, v13
	v_pk_mul_f32 v[10:11], v[10:11], v[12:13]
	v_cndmask_b32_e64 v13, 1.0, v31, s[22:23]
	v_pk_add_f32 v[14:15], v[30:31], 1.0 op_sel_hi:[1,0] neg_lo:[1,0] neg_hi:[1,0]
	v_mul_f32_e32 v31, v38, v12
	v_cndmask_b32_e64 v15, 0, v15, s[22:23]
	v_cndmask_b32_e64 v14, 0, v14, s[24:25]
	v_mul_f32_e32 v30, v13, v31
	v_pk_mul_f32 v[12:13], v[14:15], v[30:31]
	v_cndmask_b32_e64 v38, 1.0, v8, s[20:21]
	v_cndmask_b32_e64 v14, 1.0, v9, s[18:19]
	v_pk_add_f32 v[8:9], v[8:9], 1.0 op_sel_hi:[1,0] neg_lo:[1,0] neg_hi:[1,0]
	v_mul_f32_e32 v15, v39, v30
	v_cndmask_b32_e64 v9, 0, v9, s[18:19]
	v_cndmask_b32_e64 v8, 0, v8, s[20:21]
	v_mul_f32_e32 v14, v14, v15
	v_pk_mul_f32 v[30:31], v[8:9], v[14:15]
	v_mul_f32_e32 v9, v38, v14
	v_cndmask_b32_e64 v15, 1.0, v4, s[12:13]
	v_cndmask_b32_e64 v38, 1.0, v5, s[10:11]
	v_pk_add_f32 v[4:5], v[4:5], 1.0 op_sel_hi:[1,0] neg_lo:[1,0] neg_hi:[1,0]
	v_mul_f32_e32 v36, v38, v37
	v_cndmask_b32_e64 v5, 0, v5, s[10:11]
	v_cndmask_b32_e64 v4, 0, v4, s[12:13]
	v_pk_mul_f32 v[4:5], v[4:5], v[36:37]
	v_cndmask_b32_e64 v38, 1.0, v28, s[8:9]
	v_cndmask_b32_e64 v39, 1.0, v29, s[6:7]
	v_pk_add_f32 v[28:29], v[28:29], 1.0 op_sel_hi:[1,0] neg_lo:[1,0] neg_hi:[1,0]
	v_mul_f32_e32 v37, v15, v36
	v_cndmask_b32_e64 v29, 0, v29, s[6:7]
	v_cndmask_b32_e64 v28, 0, v28, s[8:9]
	v_mul_f32_e32 v36, v39, v37
	v_pk_mul_f32 v[28:29], v[28:29], v[36:37]
	v_cndmask_b32_e64 v15, 1.0, v0, s[2:3]
	v_cndmask_b32_e64 v39, 1.0, v1, s[4:5]
	v_pk_add_f32 v[0:1], v[0:1], 1.0 op_sel_hi:[1,0] neg_lo:[1,0] neg_hi:[1,0]
	v_mul_f32_e32 v37, v38, v36
	v_cndmask_b32_e64 v1, 0, v1, s[4:5]
	v_cndmask_b32_e64 v0, 0, v0, s[2:3]
	v_mul_f32_e32 v36, v39, v37
	v_pk_mul_f32 v[0:1], v[0:1], v[36:37]
	v_mul_f32_e32 v37, v15, v36
	ds_bpermute_b32 v36, v81, v37
	ds_bpermute_b32 v8, v81, v9
	s_waitcnt lgkmcnt(0)
	v_cndmask_b32_e64 v15, 1.0, v36, s[36:37]
	v_mul_f32_e32 v15, v15, v8
	v_mul_f32_e32 v38, v15, v9
	v_cndmask_b32_e64 v14, 1.0, v8, s[36:37]
	v_pk_mul_f32 v[0:1], v[0:1], v[38:39] op_sel_hi:[1,0]
	v_pk_mul_f32 v[40:41], v[28:29], v[38:39] op_sel_hi:[1,0]
	v_pk_mul_f32 v[4:5], v[4:5], v[38:39] op_sel_hi:[1,0]
	v_pk_mul_f32 v[2:3], v[2:3], v[38:39] op_sel_hi:[1,0]
	v_pk_mul_f32 v[38:39], v[14:15], v[30:31] op_sel_hi:[0,1]
	v_pk_mul_f32 v[12:13], v[14:15], v[12:13] op_sel_hi:[0,1]
	v_pk_mul_f32 v[10:11], v[14:15], v[10:11] op_sel_hi:[0,1]
	v_pk_mul_f32 v[6:7], v[14:15], v[6:7] op_sel_hi:[0,1]
	v_pk_mul_f32 v[8:9], v[36:37], v[8:9]
	v_cvt_pk_bf16_f32 v28, v0, v1
	v_cvt_pk_bf16_f32 v29, v40, v41
	v_cvt_pk_bf16_f32 v30, v4, v5
	v_cvt_pk_bf16_f32 v31, v2, v3
	v_mul_f32_e32 v97, v8, v9
	v_cvt_pk_bf16_f32 v36, v38, v39
	v_cvt_pk_bf16_f32 v37, v12, v13
	v_cvt_pk_bf16_f32 v38, v10, v11
	v_cvt_pk_bf16_f32 v39, v6, v7
	s_nop 0
	v_mfma_f32_32x32x16_bf16 v[0:15], v[24:27], v[28:31], 0
	v_cmp_gt_f32_e32 vcc, s45, v97
	s_cmp_eq_u64 vcc, exec
	s_cselect_b64 s[42:43], -1, 0
	s_cmp_eq_u32 s47, 0
	s_cselect_b64 s[48:49], -1, 0
	s_or_b64 s[42:43], s[48:49], s[42:43]
	s_and_b64 vcc, exec, s[42:43]
	s_nop 0
	v_mfma_f32_32x32x16_bf16 v[0:15], v[20:23], v[36:39], v[0:15]
	s_nop 0
	v_mfma_f32_32x32x16_bf16 v[16:31], v[16:19], v[28:31], 0
	s_nop 0
	v_mfma_f32_32x32x16_bf16 v[16:31], v[32:35], v[36:39], v[16:31]
	s_cbranch_vccnz .LBB0_400
	s_add_i32 s47, s47, -1
.Latt_T1:
	s_add_i32 s98, s47, -1
	s_max_i32 s98, s98, 0
	s_lshl_b32 s94, s98, 16
	s_add_u32 s94, s80, s94
	s_addc_u32 s95, s81, 0
	s_lshl_b32 s96, s98, 6
	s_add_u32 s96, s82, s96
	s_addc_u32 s97, s83, 0
	s_add_i32 m0, s78, 0x0
	s_nop 0
	global_load_lds_dwordx4 v190, s[94:95]
	global_load_lds_dwordx4 v191, s[94:95] offset:1024
	global_load_lds_dwordx4 v192, s[94:95] offset:2048
	global_load_lds_dwordx4 v193, s[94:95] offset:3072
	s_add_i32 m0, s78, 0x1000
	s_nop 0
	global_load_lds_dwordx4 v194, s[96:97]
	global_load_lds_dwordx4 v195, s[96:97] offset:1024
	global_load_lds_dwordx4 v196, s[96:97] offset:2048
	global_load_lds_dwordx4 v197, s[96:97] offset:3072
	s_waitcnt vmcnt(8)
	ds_read_b128 v[112:115], v198 offset:8192
	ds_read_b128 v[116:119], v199 offset:8192
	ds_read_b128 v[120:123], v200 offset:8192
	ds_read_b128 v[124:127], v201 offset:8192
	ds_read_b128 v[128:131], v202 offset:8192
	ds_read_b128 v[132:135], v203 offset:8192
	ds_read_b128 v[136:139], v204 offset:8192
	ds_read_b128 v[140:143], v205 offset:8192
	s_waitcnt lgkmcnt(7)
	v_mfma_f32_32x32x16_bf16 v[32:47], v[112:115], v[48:51], 0
	s_waitcnt lgkmcnt(6)
	v_mfma_f32_32x32x16_bf16 v[32:47], v[116:119], v[52:55], v[32:47]
	s_waitcnt lgkmcnt(5)
	v_mfma_f32_32x32x16_bf16 v[32:47], v[120:123], v[56:59], v[32:47]
	s_waitcnt lgkmcnt(4)
; __device__ __forceinline__ unsigned cvtpk(float lo, float hi) { const f32x2_t v = {lo, hi}; return __builtin_bit_cast(unsigned, __builtin_convertvector(v, bf16x2_cv)); }
; #define MFMA32(A, B, C) __builtin_amdgcn_mfma_f32_32x32x16_bf16((A), (B), (C), 0, 0, 0)
; template <bool DIAG> __device__ __forceinline__ bool attn_tile(const bf16x8_t (&Kc)[4], const bf16x8_t (&Vc)[4], const bf16x8_t (&Qf)[4], f32x16& O0, f32x16& O1, float& carry, int r32, int hi) {
;     ...
; #pragma unroll
;     for (int j = 0; j < 16; ++j) {
;         const float r = __builtin_amdgcn_rcpf(1.0f + __builtin_amdgcn_exp2f(Sx[j]));
;         if (DIAG) { const int sl = 16 * (j >> 3) + 8 * hi + (j & 7); const bool valid = sl < r32; kp[j] = valid ? r : 1.f; sg[j] = valid ? 1.0f - r : 0.f; }
;         else { kp[j] = r; sg[j] = 1.0f - r; }
;     }
; #pragma unroll
;     for (int j = 6; j >= 0; --j) { sg[j] *= kp[j + 1]; kp[j] *= kp[j + 1]; sg[8 + j] *= kp[8 + j + 1]; kp[8 + j] *= kp[8 + j + 1]; }
;     const float G0 = kp[0], G1 = kp[8];
;     const float P0 = __shfl_xor(G0, 32), P1 = __shfl_xor(G1, 32);
;     const float after0 = (hi == 0 ? P0 : 1.f) * P1 * G1 * carry, after1 = (hi == 0 ? P1 : 1.f) * carry;
; #pragma unroll
;     for (int j = 0; j < 16; ++j) sg[j] *= (j < 8 ? after0 : after1);
;     carry *= (G0 * G1) * (P0 * P1);
;     v4u w0, w1; w0.x = cvtpk(sg[0], sg[1]); w0.y = cvtpk(sg[2], sg[3]); w0.z = cvtpk(sg[4], sg[5]); w0.w = cvtpk(sg[6], sg[7]);
;     w1.x = cvtpk(sg[8], sg[9]); w1.y = cvtpk(sg[10], sg[11]); w1.z = cvtpk(sg[12], sg[13]); w1.w = cvtpk(sg[14], sg[15]);
;     const bf16x8_t Pb0 = __builtin_bit_cast(bf16x8_t, w0), Pb1 = __builtin_bit_cast(bf16x8_t, w1);
;     O0 = MFMA32(Vc[0], Pb0, O0); O0 = MFMA32(Vc[1], Pb1, O0);
;     O1 = MFMA32(Vc[2], Pb0, O1); O1 = MFMA32(Vc[3], Pb1, O1);
;     return __all(carry < 0x1p-134f);
; __device__ __forceinline__ void attn_mfma(const Args& a, int u0, int ucnt, int ustride) {
;     ...
;             for (;;) {
;                 ATT_LOAD(KA, VA, kb > 0 ? kb - 1 : 0);
;                 if (attn_tile<false>(KB, VB, Qf, O0, O1, carry, r32, hi) || kb == 0) break;
	v_mfma_f32_32x32x16_bf16 v[32:47], v[124:127], v[60:63], v[32:47]
	s_nop 11
	v_exp_f32_e32 v36, v36
	v_exp_f32_e32 v47, v47
	v_exp_f32_e32 v35, v35
	v_exp_f32_e32 v34, v34
	v_add_f32_e32 v36, 1.0, v36
	v_rcp_f32_e32 v98, v36
	v_exp_f32_e32 v36, v37
	v_add_f32_e32 v47, 1.0, v47
	v_rcp_f32_e32 v83, v47
	v_exp_f32_e32 v33, v33
	v_add_f32_e32 v36, 1.0, v36
	v_rcp_f32_e32 v99, v36
	v_exp_f32_e32 v36, v38
	v_exp_f32_e32 v38, v39
	v_exp_f32_e32 v32, v32
	v_add_f32_e32 v35, 1.0, v35
	v_add_f32_e32 v36, 1.0, v36
	v_add_f32_e32 v38, 1.0, v38
	v_rcp_f32_e32 v96, v38
	v_exp_f32_e32 v38, v40
	v_rcp_f32_e32 v37, v36
	v_add_f32_e32 v34, 1.0, v34
	v_rcp_f32_e32 v35, v35
	v_add_f32_e32 v38, 1.0, v38
	v_rcp_f32_e32 v40, v38
	v_exp_f32_e32 v38, v41
	v_add_f32_e32 v33, 1.0, v33
	v_rcp_f32_e32 v34, v34
	v_add_f32_e32 v32, 1.0, v32
	v_add_f32_e32 v38, 1.0, v38
	v_rcp_f32_e32 v41, v38
	v_exp_f32_e32 v38, v42
	v_rcp_f32_e32 v33, v33
	v_rcp_f32_e32 v32, v32
	v_pk_add_f32 v[106:107], v[34:35], 1.0 op_sel_hi:[1,0] neg_lo:[1,0] neg_hi:[1,0]
	v_add_f32_e32 v38, 1.0, v38
	v_rcp_f32_e32 v42, v38
	v_exp_f32_e32 v38, v43
	v_sub_f32_e32 v36, 1.0, v37
	v_sub_f32_e32 v39, 1.0, v96
	v_sub_f32_e32 v47, 1.0, v83
	v_add_f32_e32 v38, 1.0, v38
	v_rcp_f32_e32 v43, v38
	v_exp_f32_e32 v38, v44
	v_pk_add_f32 v[104:105], v[42:43], 1.0 op_sel_hi:[1,0] neg_lo:[1,0] neg_hi:[1,0]
	v_add_f32_e32 v38, 1.0, v38
	v_rcp_f32_e32 v44, v38
	v_exp_f32_e32 v38, v45
	s_nop 0
	v_add_f32_e32 v38, 1.0, v38
	v_rcp_f32_e32 v45, v38
	v_exp_f32_e32 v38, v46
	v_pk_add_f32 v[100:101], v[44:45], 1.0 op_sel_hi:[1,0] neg_lo:[1,0] neg_hi:[1,0]
	v_add_f32_e32 v38, 1.0, v38
	v_rcp_f32_e32 v38, v38
	s_nop 0
	v_mul_f32_e32 v103, v38, v83
	v_mul_f32_e32 v102, v45, v103
	v_mul_f32_e32 v45, v44, v102
	v_mul_f32_e32 v44, v43, v45
	v_mul_f32_e32 v43, v42, v44
	v_pk_mul_f32 v[100:101], v[100:101], v[102:103]
	v_pk_mul_f32 v[102:103], v[104:105], v[44:45]
	v_pk_add_f32 v[104:105], v[40:41], 1.0 op_sel_hi:[1,0] neg_lo:[1,0] neg_hi:[1,0]
	v_mul_f32_e32 v42, v41, v43
	v_pk_mul_f32 v[44:45], v[104:105], v[42:43]
	v_mul_f32_e32 v105, v37, v96
	v_mul_f32_e32 v104, v99, v105
	v_mul_f32_e32 v41, v40, v42
	v_pk_add_f32 v[42:43], v[98:99], 1.0 op_sel_hi:[1,0] neg_lo:[1,0] neg_hi:[1,0]
	v_mul_f32_e32 v99, v98, v104
	v_mul_f32_e32 v98, v35, v99
	v_mul_f32_e32 v35, v34, v98
	v_mul_f32_e32 v34, v33, v35
	v_pk_mul_f32 v[42:43], v[42:43], v[104:105]
	v_pk_mul_f32 v[104:105], v[106:107], v[98:99]
	v_pk_add_f32 v[106:107], v[32:33], 1.0 op_sel_hi:[1,0] neg_lo:[1,0] neg_hi:[1,0]
	v_mul_f32_e32 v33, v32, v34
	ds_bpermute_b32 v32, v81, v33
	ds_bpermute_b32 v40, v81, v41
	v_pk_mul_f32 v[98:99], v[106:107], v[34:35]
	v_sub_f32_e32 v46, 1.0, v38
	v_mul_f32_e32 v46, v83, v46
	s_waitcnt lgkmcnt(1)
	v_cndmask_b32_e64 v34, 1.0, v32, s[36:37]
	s_waitcnt lgkmcnt(0)
	v_mul_f32_e32 v34, v34, v40
	v_mul_f32_e32 v37, v34, v41
	v_pk_mul_f32 v[34:35], v[96:97], v[36:37]
	v_cndmask_b32_e64 v83, 1.0, v40, s[36:37]
	v_mov_b32_e32 v38, v35
	v_pk_mul_f32 v[32:33], v[32:33], v[40:41]
	v_pk_mul_f32 v[36:37], v[98:99], v[34:35] op_sel:[0,1]
	v_pk_mul_f32 v[98:99], v[104:105], v[34:35] op_sel:[0,1]
	v_pk_mul_f32 v[42:43], v[42:43], v[34:35] op_sel:[0,1]
	v_pk_mul_f32 v[38:39], v[34:35], v[38:39]
	v_mul_f32_e32 v34, v97, v83
	v_mul_f32_e32 v32, v32, v33
	v_pk_mul_f32 v[44:45], v[34:35], v[44:45] op_sel_hi:[0,1]
	v_pk_mul_f32 v[102:103], v[34:35], v[102:103] op_sel_hi:[0,1]
	v_pk_mul_f32 v[100:101], v[34:35], v[100:101] op_sel_hi:[0,1]
	v_pk_mul_f32 v[46:47], v[34:35], v[46:47] op_sel_hi:[0,1]
	v_mul_f32_e32 v97, v97, v32
	v_cvt_pk_bf16_f32 v32, v36, v37
	v_cvt_pk_bf16_f32 v33, v98, v99
	v_cvt_pk_bf16_f32 v34, v42, v43
	v_cvt_pk_bf16_f32 v35, v38, v39
	v_cvt_pk_bf16_f32 v36, v44, v45
	v_cvt_pk_bf16_f32 v37, v102, v103
	v_mfma_f32_32x32x16_bf16 v[0:15], v[128:131], v[32:35], v[0:15]
	v_cvt_pk_bf16_f32 v38, v100, v101
	v_cvt_pk_bf16_f32 v39, v46, v47
	v_cmp_gt_f32_e32 vcc, s45, v97
	s_cmp_eq_u64 vcc, exec
	s_cselect_b64 s[42:43], -1, 0
	s_cmp_eq_u32 s47, 0
	s_cselect_b64 s[48:49], -1, 0
	v_mfma_f32_32x32x16_bf16 v[16:31], v[136:139], v[32:35], v[16:31]
	s_or_b64 s[48:49], s[48:49], s[42:43]
	s_and_b64 vcc, exec, s[48:49]
	v_mfma_f32_32x32x16_bf16 v[0:15], v[132:135], v[36:39], v[0:15]
	v_mfma_f32_32x32x16_bf16 v[16:31], v[140:143], v[36:39], v[16:31]
	s_cbranch_vccnz .Latt_exit
	s_add_i32 s47, s47, -1
; #define ATT_LOAD(K_, V_, kb_) do { _Pragma("unroll") for (int ks = 0; ks < 4; ++ks) K_[ks] = *(const bf16x8_t*)(kbase + (size_t)(32 * (kb_)) * 1024 + 16 * ks); \
;         _Pragma("unroll") for (int i = 0; i < 4; ++i) V_[i] = *(const bf16x8_t*)(vbase + (size_t)(32 * (i >> 1)) * 2048 + 32 * (kb_) + 16 * (i & 1)); } while (0)
; __device__ __forceinline__ ConvItem conv_item(const Args& a, unsigned char* ws, int it) {
;     constexpr int I_IN = 16 * (INW / 32), I_SQ = 16 * 32, I_F1 = 16 * (2 * FFH / 32);
;     ConvItem p; int r = it; p.ks = nullptr; p.koff = 0; p.cs = 1.0f;
;     if (r < I_IN) { const int nblk = INW / 32, kb = r / nblk, nb = r % nblk, n0d = 32 * nb; const int sec = n0d >> 10; int n0s = n0d;
;         if (sec == 4 || sec == 5) { const int q = n0d & 255; n0s = (n0d - q) + 64 * ((q >> 5) & 3) + 32 * (q >> 7); }
;         p.W = a.in[2]; p.N = INW; p.WT = (bf16*)(ws + WS_WIN); p.ldT = 1024; p.k0 = 64 * kb; p.n0d = n0d; p.n0s = n0s; if (sec == 1 || sec == 3 || sec >= 7) p.cs = -1.4426950408889634f; return p; } r -= I_IN;
; __device__ __forceinline__ void attn_mfma(const Args& a, int u0, int ucnt, int ustride) {
;     ...
;             for (;;) {
;                 ATT_LOAD(KA, VA, kb > 0 ? kb - 1 : 0);
;                 if (attn_tile<false>(KB, VB, Qf, O0, O1, carry, r32, hi) || kb == 0) break;
;     ...
;                 ATT_LOAD(KB, VB, kb > 0 ? kb - 1 : 0);
;                 if (attn_tile<false>(KA, VA, Qf, O0, O1, carry, r32, hi) || kb == 0) break;
;     ...
;             }
;         }
.Latt_T0:
	s_add_i32 s98, s47, -1
	s_max_i32 s98, s98, 0
	s_lshl_b32 s94, s98, 16
	s_add_u32 s94, s80, s94
	s_addc_u32 s95, s81, 0
	s_lshl_b32 s96, s98, 6
	s_add_u32 s96, s82, s96
	s_addc_u32 s97, s83, 0
	s_add_i32 m0, s78, 0x2000
	s_nop 0
	global_load_lds_dwordx4 v190, s[94:95]
	global_load_lds_dwordx4 v191, s[94:95] offset:1024
	global_load_lds_dwordx4 v192, s[94:95] offset:2048
	global_load_lds_dwordx4 v193, s[94:95] offset:3072
	s_add_i32 m0, s78, 0x3000
	s_nop 0
	global_load_lds_dwordx4 v194, s[96:97]
	global_load_lds_dwordx4 v195, s[96:97] offset:1024
	global_load_lds_dwordx4 v196, s[96:97] offset:2048
	global_load_lds_dwordx4 v197, s[96:97] offset:3072
	s_waitcnt vmcnt(8)
	ds_read_b128 v[112:115], v198
	ds_read_b128 v[116:119], v199
	ds_read_b128 v[120:123], v200
	ds_read_b128 v[124:127], v201
	ds_read_b128 v[128:131], v202
	ds_read_b128 v[132:135], v203
	ds_read_b128 v[136:139], v204
	ds_read_b128 v[140:143], v205
	s_waitcnt lgkmcnt(7)
	v_mfma_f32_32x32x16_bf16 v[32:47], v[112:115], v[48:51], 0
	s_waitcnt lgkmcnt(6)
	v_mfma_f32_32x32x16_bf16 v[32:47], v[116:119], v[52:55], v[32:47]
	s_waitcnt lgkmcnt(5)
	v_mfma_f32_32x32x16_bf16 v[32:47], v[120:123], v[56:59], v[32:47]
	s_waitcnt lgkmcnt(4)
	v_mfma_f32_32x32x16_bf16 v[32:47], v[124:127], v[60:63], v[32:47]
	s_nop 11
	v_exp_f32_e32 v36, v36
	v_exp_f32_e32 v47, v47
	v_exp_f32_e32 v35, v35
	v_exp_f32_e32 v34, v34
	v_add_f32_e32 v36, 1.0, v36
	v_rcp_f32_e32 v98, v36
	v_exp_f32_e32 v36, v37
	v_add_f32_e32 v47, 1.0, v47
	v_rcp_f32_e32 v83, v47
	v_exp_f32_e32 v33, v33
	v_add_f32_e32 v36, 1.0, v36
	v_rcp_f32_e32 v99, v36
	v_exp_f32_e32 v36, v38
	v_exp_f32_e32 v38, v39
	v_exp_f32_e32 v32, v32
	v_add_f32_e32 v35, 1.0, v35
	v_add_f32_e32 v36, 1.0, v36
	v_add_f32_e32 v38, 1.0, v38
	v_rcp_f32_e32 v96, v38
	v_exp_f32_e32 v38, v40
	v_rcp_f32_e32 v37, v36
	v_add_f32_e32 v34, 1.0, v34
	v_rcp_f32_e32 v35, v35
	v_add_f32_e32 v38, 1.0, v38
	v_rcp_f32_e32 v40, v38
	v_exp_f32_e32 v38, v41
	v_add_f32_e32 v33, 1.0, v33
	v_rcp_f32_e32 v34, v34
	v_add_f32_e32 v32, 1.0, v32
	v_add_f32_e32 v38, 1.0, v38
	v_rcp_f32_e32 v41, v38
	v_exp_f32_e32 v38, v42
	v_rcp_f32_e32 v33, v33
	v_rcp_f32_e32 v32, v32
	v_pk_add_f32 v[106:107], v[34:35], 1.0 op_sel_hi:[1,0] neg_lo:[1,0] neg_hi:[1,0]
	v_add_f32_e32 v38, 1.0, v38
	v_rcp_f32_e32 v42, v38
	v_exp_f32_e32 v38, v43
	v_sub_f32_e32 v36, 1.0, v37
	v_sub_f32_e32 v39, 1.0, v96
	v_sub_f32_e32 v47, 1.0, v83
	v_add_f32_e32 v38, 1.0, v38
	v_rcp_f32_e32 v43, v38
	v_exp_f32_e32 v38, v44
	v_pk_add_f32 v[104:105], v[42:43], 1.0 op_sel_hi:[1,0] neg_lo:[1,0] neg_hi:[1,0]
	v_add_f32_e32 v38, 1.0, v38
	v_rcp_f32_e32 v44, v38
	v_exp_f32_e32 v38, v45
	s_nop 0
	v_add_f32_e32 v38, 1.0, v38
	v_rcp_f32_e32 v45, v38
	v_exp_f32_e32 v38, v46
	v_pk_add_f32 v[100:101], v[44:45], 1.0 op_sel_hi:[1,0] neg_lo:[1,0] neg_hi:[1,0]
	v_add_f32_e32 v38, 1.0, v38
	v_rcp_f32_e32 v38, v38
	s_nop 0
	v_mul_f32_e32 v103, v38, v83
	v_mul_f32_e32 v102, v45, v103
	v_mul_f32_e32 v45, v44, v102
	v_mul_f32_e32 v44, v43, v45
	v_mul_f32_e32 v43, v42, v44
	v_pk_mul_f32 v[100:101], v[100:101], v[102:103]
	v_pk_mul_f32 v[102:103], v[104:105], v[44:45]
	v_pk_add_f32 v[104:105], v[40:41], 1.0 op_sel_hi:[1,0] neg_lo:[1,0] neg_hi:[1,0]
	v_mul_f32_e32 v42, v41, v43
	v_pk_mul_f32 v[44:45], v[104:105], v[42:43]
	v_mul_f32_e32 v105, v37, v96
	v_mul_f32_e32 v104, v99, v105
	v_mul_f32_e32 v41, v40, v42
	v_pk_add_f32 v[42:43], v[98:99], 1.0 op_sel_hi:[1,0] neg_lo:[1,0] neg_hi:[1,0]
	v_mul_f32_e32 v99, v98, v104
	v_mul_f32_e32 v98, v35, v99
	v_mul_f32_e32 v35, v34, v98
	v_mul_f32_e32 v34, v33, v35
	v_pk_mul_f32 v[42:43], v[42:43], v[104:105]
	v_pk_mul_f32 v[104:105], v[106:107], v[98:99]
	v_pk_add_f32 v[106:107], v[32:33], 1.0 op_sel_hi:[1,0] neg_lo:[1,0] neg_hi:[1,0]
	v_mul_f32_e32 v33, v32, v34
	ds_bpermute_b32 v32, v81, v33
	ds_bpermute_b32 v40, v81, v41
	v_pk_mul_f32 v[98:99], v[106:107], v[34:35]
	v_sub_f32_e32 v46, 1.0, v38
	v_mul_f32_e32 v46, v83, v46
	s_waitcnt lgkmcnt(1)
	v_cndmask_b32_e64 v34, 1.0, v32, s[36:37]
	s_waitcnt lgkmcnt(0)
	v_mul_f32_e32 v34, v34, v40
	v_mul_f32_e32 v37, v34, v41
	v_pk_mul_f32 v[34:35], v[96:97], v[36:37]
	v_cndmask_b32_e64 v83, 1.0, v40, s[36:37]
	v_mov_b32_e32 v38, v35
	v_pk_mul_f32 v[32:33], v[32:33], v[40:41]
	v_pk_mul_f32 v[36:37], v[98:99], v[34:35] op_sel:[0,1]
	v_pk_mul_f32 v[98:99], v[104:105], v[34:35] op_sel:[0,1]
	v_pk_mul_f32 v[42:43], v[42:43], v[34:35] op_sel:[0,1]
	v_pk_mul_f32 v[38:39], v[34:35], v[38:39]
	v_mul_f32_e32 v34, v97, v83
	v_mul_f32_e32 v32, v32, v33
	v_pk_mul_f32 v[44:45], v[34:35], v[44:45] op_sel_hi:[0,1]
	v_pk_mul_f32 v[102:103], v[34:35], v[102:103] op_sel_hi:[0,1]
	v_pk_mul_f32 v[100:101], v[34:35], v[100:101] op_sel_hi:[0,1]
	v_pk_mul_f32 v[46:47], v[34:35], v[46:47] op_sel_hi:[0,1]
	v_mul_f32_e32 v97, v97, v32
	v_cvt_pk_bf16_f32 v32, v36, v37
	v_cvt_pk_bf16_f32 v33, v98, v99
	v_cvt_pk_bf16_f32 v34, v42, v43
	v_cvt_pk_bf16_f32 v35, v38, v39
	v_cvt_pk_bf16_f32 v36, v44, v45
	v_cvt_pk_bf16_f32 v37, v102, v103
	v_mfma_f32_32x32x16_bf16 v[0:15], v[128:131], v[32:35], v[0:15]
	v_cvt_pk_bf16_f32 v38, v100, v101
	v_cvt_pk_bf16_f32 v39, v46, v47
	v_cmp_gt_f32_e32 vcc, s45, v97
	s_cmp_eq_u64 vcc, exec
	s_cselect_b64 s[42:43], -1, 0
	s_cmp_eq_u32 s47, 0
	s_cselect_b64 s[48:49], -1, 0
	v_mfma_f32_32x32x16_bf16 v[16:31], v[136:139], v[32:35], v[16:31]
	s_or_b64 s[48:49], s[48:49], s[42:43]
	s_and_b64 vcc, exec, s[48:49]
	v_mfma_f32_32x32x16_bf16 v[0:15], v[132:135], v[36:39], v[0:15]
	v_mfma_f32_32x32x16_bf16 v[16:31], v[140:143], v[36:39], v[16:31]
	s_cbranch_vccnz .Latt_exit
	s_add_i32 s47, s47, -1
	s_branch .Latt_T1
.Latt_exit:
	s_nop 3
	s_branch .LBB0_400
.LBB0_406:
	s_cbranch_execnz .LBB0_547
	s_branch .LBB0_667
.LBB0_407:
	s_waitcnt vmcnt(0)
.LBB0_408:
	s_sub_i32 s46, s33, 64
.LBB0_416:
	s_mov_b64 s[2:3], -1
	s_and_b64 vcc, exec, s[0:1]
	s_cbranch_vccz .LBB0_511
	s_lshl_b32 s0, s33, 3
	v_readlane_b32 s1, v254, 11
	s_add_i32 s0, s0, s1
	s_addk_i32 s0, 0x200
	s_cmpk_gt_i32 s0, 0x167f
	s_cbranch_scc1 .LBB0_510
	s_add_i32 s40, s0, 0x1200
	s_cmp_gt_i32 s0, -1
	s_cbranch_scc0 .LBB0_425
	s_cmpk_gt_u32 s40, 0x13ff
	s_cbranch_scc0 .LBB0_426
	s_cmpk_gt_u32 s40, 0x15ff
	s_cbranch_scc0 .LBB0_427
	s_cmpk_gt_u32 s40, 0x17ff
	s_cbranch_scc0 .LBB0_428
	s_cmpk_gt_u32 s40, 0x22ff
	s_cbranch_scc0 .LBB0_429
	s_add_u32 s8, s72, 0x2500000
	s_addc_u32 s9, s73, 0
	s_lshl_b32 s0, s40, 1
	s_add_i32 s0, s0, 0x7fffba00
	s_and_b32 s4, s0, 0x7fffffc0
	s_lshl_b32 s0, s40, 5
	s_and_b32 s10, s0, 0x3e0
	s_mov_b64 s[6:7], 0
	s_mov_b64 s[0:1], 0
	s_mov_b64 s[2:3], s[68:69]
	s_branch .LBB0_430

; __global__ void __launch_bounds__(NTHREADS, 2) hybrid_fwd(Args args) {
	.amdhsa_kernel _Z10hybrid_fwd4Args
		.amdhsa_group_segment_fixed_size 0
		.amdhsa_private_segment_fixed_size 0
		.amdhsa_kernarg_size 384
		.amdhsa_user_sgpr_count 2
		.amdhsa_user_sgpr_dispatch_ptr 0
		.amdhsa_user_sgpr_queue_ptr 0
		.amdhsa_user_sgpr_kernarg_segment_ptr 1
		.amdhsa_user_sgpr_dispatch_id 0
		.amdhsa_user_sgpr_kernarg_preload_length 0
		.amdhsa_user_sgpr_kernarg_preload_offset 0
		.amdhsa_user_sgpr_private_segment_size 0
		.amdhsa_uses_dynamic_stack 0
		.amdhsa_enable_private_segment 0
		.amdhsa_system_sgpr_workgroup_id_x 1
		.amdhsa_system_sgpr_workgroup_id_y 0
		.amdhsa_system_sgpr_workgroup_id_z 0
		.amdhsa_system_sgpr_workgroup_info 0
		.amdhsa_system_vgpr_workitem_id 2
		.amdhsa_next_free_vgpr 255
		.amdhsa_next_free_sgpr 102
		.amdhsa_accum_offset 256
		.amdhsa_reserve_vcc 1
		.amdhsa_float_round_mode_32 0
		.amdhsa_float_round_mode_16_64 0
		.amdhsa_float_denorm_mode_32 3
		.amdhsa_float_denorm_mode_16_64 3
		.amdhsa_dx10_clamp 1
		.amdhsa_ieee_mode 1
		.amdhsa_fp16_overflow 0
		.amdhsa_tg_split 0
		.amdhsa_exception_fp_ieee_invalid_op 0
		.amdhsa_exception_fp_denorm_src 0
		.amdhsa_exception_fp_ieee_div_zero 0
		.amdhsa_exception_fp_ieee_overflow 0
		.amdhsa_exception_fp_ieee_underflow 0
		.amdhsa_exception_fp_ieee_inexact 0
		.amdhsa_exception_int_div_zero 0
	.end_amdhsa_kernel

; __global__ void __launch_bounds__(NTHREADS, 2) hybrid_fwd(Args args) {
amdhsa.kernels:
  - .agpr_count:     0
    .args:
      - .offset:         0
        .size:           128
        .value_kind:     by_value
      - .offset:         128
        .size:           4
        .value_kind:     hidden_block_count_x
      - .offset:         132
        .size:           4
        .value_kind:     hidden_block_count_y
      - .offset:         136
        .size:           4
        .value_kind:     hidden_block_count_z
      - .offset:         140
        .size:           2
        .value_kind:     hidden_group_size_x
      - .offset:         142
        .size:           2
        .value_kind:     hidden_group_size_y
      - .offset:         144
        .size:           2
        .value_kind:     hidden_group_size_z
      - .offset:         146
        .size:           2
        .value_kind:     hidden_remainder_x
      - .offset:         148
        .size:           2
        .value_kind:     hidden_remainder_y
      - .offset:         150
        .size:           2
        .value_kind:     hidden_remainder_z
      - .offset:         168
        .size:           8
        .value_kind:     hidden_global_offset_x
      - .offset:         176
        .size:           8
        .value_kind:     hidden_global_offset_y
      - .offset:         184
        .size:           8
        .value_kind:     hidden_global_offset_z
      - .offset:         192
        .size:           2
        .value_kind:     hidden_grid_dims
      - .offset:         216
        .size:           8
        .value_kind:     hidden_multigrid_sync_arg
      - .offset:         248
        .size:           4
        .value_kind:     hidden_dynamic_lds_size
    .group_segment_fixed_size: 0
    .kernarg_segment_align: 8
    .kernarg_segment_size: 384
    .language:       OpenCL C
    .language_version:
      - 2
      - 0
    .max_flat_workgroup_size: 512
    .name:           _Z10hybrid_fwd4Args
    .private_segment_fixed_size: 0
    .sgpr_count:     108
    .sgpr_spill_count: 34
    .symbol:         _Z10hybrid_fwd4Args.kd
    .uniform_work_group_size: 1
    .uses_dynamic_stack: false
    .vgpr_count:     255
    .vgpr_spill_count: 0
    .wavefront_size: 64
